# grid barrier: non-leader workgroups poll the top generation word directly instead of the per-XCD generation word (one hop less)
# speedup vs baseline: 1.0038x; 1.0017x over previous
; __device__ __forceinline__ unsigned xb_ld(unsigned* p)              { return __hip_atomic_load(p, __ATOMIC_RELAXED, __HIP_MEMORY_SCOPE_AGENT); }
; __device__ __forceinline__ unsigned xb_add(unsigned* p, unsigned v) { return __hip_atomic_fetch_add(p, v, __ATOMIC_RELAXED, __HIP_MEMORY_SCOPE_AGENT); }
; #define XB_SPIN(cond, bar) do { unsigned _sp = 0; while (cond) { __builtin_amdgcn_s_sleep(1); \
;     if ((++_sp & 255u) == 0u) { if (xb_ld(&(bar)[XB_TMO])) break; if (_sp > XB_SPIN_CAP) { atomicAdd(&(bar)[XB_TMO], 1u); break; } } } } while (0)
; __device__ __forceinline__ void xcd_barrier(const XcdBarrier& b) {
;     ...
;         const unsigned old = xb_add(&bar[XB_XSUB(b.x)], 1u);
;         const unsigned gen = old / nloc;
;         if (old + 1u == (gen + 1u) * nloc) {
;             __builtin_amdgcn_fence(__ATOMIC_RELEASE, "agent");
;             asm volatile("s_waitcnt vmcnt(0)" ::: "memory");
;             const unsigned og = xb_add(&bar[XB_TOP], 1u);
;             const unsigned tg = og / nx;
;             if (og + 1u == (tg + 1u) * nx) xb_add(&bar[XB_TOPGEN], 1u);
;             else XB_SPIN(xb_ld(&bar[XB_TOPGEN]) == tg, bar);
;             __builtin_amdgcn_fence(__ATOMIC_ACQUIRE, "agent");
;             xb_add(&bar[XB_XGEN(b.x)], 1u);
;             asm volatile("s_waitcnt vmcnt(0)" ::: "memory");
;         } else {
;             XB_SPIN(xb_ld(&bar[XB_XGEN(b.x)]) == gen, bar);
;             __builtin_amdgcn_fence(__ATOMIC_ACQUIRE, "agent");
;             asm volatile("s_waitcnt vmcnt(0)" ::: "memory");
;         }
.LBB0_81:
	s_or_b64 exec, exec, s[8:9]
	v_cvt_f32_u32_e32 v4, v2
	s_waitcnt vmcnt(0)
	v_readfirstlane_b32 s2, v3
	v_sub_u32_e32 v3, 0, v2
	v_rcp_iflag_f32_e32 v4, v4
	v_add_u32_e32 v5, s2, v1
	v_mul_f32_e32 v4, 0x4f7ffffe, v4
	v_cvt_u32_f32_e32 v4, v4
	v_mul_lo_u32 v1, v3, v4
	v_mul_hi_u32 v1, v4, v1
	v_add_u32_e32 v1, v4, v1
	v_mul_hi_u32 v1, v5, v1
	v_mul_lo_u32 v3, v1, v2
	v_sub_u32_e32 v3, v5, v3
	v_add_u32_e32 v4, 1, v1
	v_cmp_ge_u32_e32 vcc, v3, v2
	s_nop 1
	v_cndmask_b32_e32 v1, v1, v4, vcc
	v_sub_u32_e32 v4, v3, v2
	v_cndmask_b32_e32 v3, v3, v4, vcc
	v_add_u32_e32 v4, 1, v1
	v_cmp_ge_u32_e32 vcc, v3, v2
	v_add_u32_e32 v3, 1, v5
	s_nop 0
	v_cndmask_b32_e32 v1, v1, v4, vcc
	v_mul_lo_u32 v4, v2, v1
	v_add_u32_e32 v2, v4, v2
	v_cmp_ne_u32_e32 vcc, v3, v2
	s_and_saveexec_b64 s[2:3], vcc
	s_xor_b64 s[6:7], exec, s[2:3]
	s_cbranch_execz .LBB0_95
	s_waitcnt lgkmcnt(0)
	v_mov_b32_e32 v0, 0x583100
	global_load_dword v0, v0, s[72:73] offset:1024 sc1
	s_add_u32 s12, s72, 0x583500
	s_addc_u32 s13, s73, 0
	s_waitcnt vmcnt(0)
	v_cmp_eq_u32_e32 vcc, v0, v1
	s_and_saveexec_b64 s[8:9], vcc
	s_cbranch_execz .LBB0_94
	s_add_u32 s10, s72, 0x580200
	s_addc_u32 s11, s73, 0
	s_mov_b32 s2, 1
	s_mov_b64 s[14:15], 0
	v_mov_b32_e32 v0, 0
	s_branch .LBB0_85

; __device__ __forceinline__ unsigned xb_ld(unsigned* p)              { return __hip_atomic_load(p, __ATOMIC_RELAXED, __HIP_MEMORY_SCOPE_AGENT); }
; __device__ __forceinline__ unsigned xb_add(unsigned* p, unsigned v) { return __hip_atomic_fetch_add(p, v, __ATOMIC_RELAXED, __HIP_MEMORY_SCOPE_AGENT); }
; #define XB_SPIN(cond, bar) do { unsigned _sp = 0; while (cond) { __builtin_amdgcn_s_sleep(1); \
;     if ((++_sp & 255u) == 0u) { if (xb_ld(&(bar)[XB_TMO])) break; if (_sp > XB_SPIN_CAP) { atomicAdd(&(bar)[XB_TMO], 1u); break; } } } } while (0)
; __device__ __forceinline__ void xcd_barrier(const XcdBarrier& b) {
;     ...
;         const unsigned old = xb_add(&bar[XB_XSUB(b.x)], 1u);
;         const unsigned gen = old / nloc;
;         if (old + 1u == (gen + 1u) * nloc) {
;             __builtin_amdgcn_fence(__ATOMIC_RELEASE, "agent");
;             asm volatile("s_waitcnt vmcnt(0)" ::: "memory");
;             const unsigned og = xb_add(&bar[XB_TOP], 1u);
;             const unsigned tg = og / nx;
;             if (og + 1u == (tg + 1u) * nx) xb_add(&bar[XB_TOPGEN], 1u);
;             else XB_SPIN(xb_ld(&bar[XB_TOPGEN]) == tg, bar);
;             __builtin_amdgcn_fence(__ATOMIC_ACQUIRE, "agent");
;             xb_add(&bar[XB_XGEN(b.x)], 1u);
;             asm volatile("s_waitcnt vmcnt(0)" ::: "memory");
;         } else {
;             XB_SPIN(xb_ld(&bar[XB_XGEN(b.x)]) == gen, bar);
;             __builtin_amdgcn_fence(__ATOMIC_ACQUIRE, "agent");
;             asm volatile("s_waitcnt vmcnt(0)" ::: "memory");
;         }
.LBB0_413:
	s_or_b64 exec, exec, s[8:9]
	v_cvt_f32_u32_e32 v4, v2
	s_waitcnt vmcnt(0)
	v_readfirstlane_b32 s2, v3
	v_sub_u32_e32 v3, 0, v2
	v_rcp_iflag_f32_e32 v4, v4
	v_add_u32_e32 v5, s2, v1
	v_mul_f32_e32 v4, 0x4f7ffffe, v4
	v_cvt_u32_f32_e32 v4, v4
	v_mul_lo_u32 v1, v3, v4
	v_mul_hi_u32 v1, v4, v1
	v_add_u32_e32 v1, v4, v1
	v_mul_hi_u32 v1, v5, v1
	v_mul_lo_u32 v3, v1, v2
	v_sub_u32_e32 v3, v5, v3
	v_add_u32_e32 v4, 1, v1
	v_cmp_ge_u32_e32 vcc, v3, v2
	s_nop 1
	v_cndmask_b32_e32 v1, v1, v4, vcc
	v_sub_u32_e32 v4, v3, v2
	v_cndmask_b32_e32 v3, v3, v4, vcc
	v_add_u32_e32 v4, 1, v1
	v_cmp_ge_u32_e32 vcc, v3, v2
	v_add_u32_e32 v3, 1, v5
	s_nop 0
	v_cndmask_b32_e32 v1, v1, v4, vcc
	v_mul_lo_u32 v4, v2, v1
	v_add_u32_e32 v2, v4, v2
	v_cmp_ne_u32_e32 vcc, v3, v2
	s_and_saveexec_b64 s[2:3], vcc
	s_xor_b64 s[6:7], exec, s[2:3]
	s_cbranch_execz .LBB0_427
	s_waitcnt lgkmcnt(0)
	v_mov_b32_e32 v0, 0x583100
	global_load_dword v0, v0, s[72:73] offset:1024 sc1
	s_add_u32 s12, s72, 0x583500
	s_addc_u32 s13, s73, 0
	s_waitcnt vmcnt(0)
	v_cmp_eq_u32_e32 vcc, v0, v1
	s_and_saveexec_b64 s[8:9], vcc
	s_cbranch_execz .LBB0_426
	s_add_u32 s10, s72, 0x580200
	s_addc_u32 s11, s73, 0
	s_mov_b32 s2, 1
	s_mov_b64 s[16:17], 0
	v_mov_b32_e32 v0, 0
	s_branch .LBB0_417

; __device__ __forceinline__ unsigned xb_ld(unsigned* p)              { return __hip_atomic_load(p, __ATOMIC_RELAXED, __HIP_MEMORY_SCOPE_AGENT); }
; __device__ __forceinline__ unsigned xb_add(unsigned* p, unsigned v) { return __hip_atomic_fetch_add(p, v, __ATOMIC_RELAXED, __HIP_MEMORY_SCOPE_AGENT); }
; #define XB_SPIN(cond, bar) do { unsigned _sp = 0; while (cond) { __builtin_amdgcn_s_sleep(1); \
;     if ((++_sp & 255u) == 0u) { if (xb_ld(&(bar)[XB_TMO])) break; if (_sp > XB_SPIN_CAP) { atomicAdd(&(bar)[XB_TMO], 1u); break; } } } } while (0)
; __device__ __forceinline__ void xcd_barrier(const XcdBarrier& b) {
;     ...
;         const unsigned old = xb_add(&bar[XB_XSUB(b.x)], 1u);
;         const unsigned gen = old / nloc;
;         if (old + 1u == (gen + 1u) * nloc) {
;             __builtin_amdgcn_fence(__ATOMIC_RELEASE, "agent");
;             asm volatile("s_waitcnt vmcnt(0)" ::: "memory");
;             const unsigned og = xb_add(&bar[XB_TOP], 1u);
;             const unsigned tg = og / nx;
;             if (og + 1u == (tg + 1u) * nx) xb_add(&bar[XB_TOPGEN], 1u);
;             else XB_SPIN(xb_ld(&bar[XB_TOPGEN]) == tg, bar);
;             __builtin_amdgcn_fence(__ATOMIC_ACQUIRE, "agent");
;             xb_add(&bar[XB_XGEN(b.x)], 1u);
;             asm volatile("s_waitcnt vmcnt(0)" ::: "memory");
;         } else {
;             XB_SPIN(xb_ld(&bar[XB_XGEN(b.x)]) == gen, bar);
;             __builtin_amdgcn_fence(__ATOMIC_ACQUIRE, "agent");
;             asm volatile("s_waitcnt vmcnt(0)" ::: "memory");
;         }
.LBB0_1080:
	s_or_b64 exec, exec, s[10:11]
	v_cvt_f32_u32_e32 v4, v2
	s_waitcnt vmcnt(0)
	v_readfirstlane_b32 s2, v3
	v_sub_u32_e32 v3, 0, v2
	v_rcp_iflag_f32_e32 v4, v4
	v_add_u32_e32 v5, s2, v1
	v_mul_f32_e32 v4, 0x4f7ffffe, v4
	v_cvt_u32_f32_e32 v4, v4
	v_mul_lo_u32 v1, v3, v4
	v_mul_hi_u32 v1, v4, v1
	v_add_u32_e32 v1, v4, v1
	v_mul_hi_u32 v1, v5, v1
	v_mul_lo_u32 v3, v1, v2
	v_sub_u32_e32 v3, v5, v3
	v_add_u32_e32 v4, 1, v1
	v_cmp_ge_u32_e32 vcc, v3, v2
	s_nop 1
	v_cndmask_b32_e32 v1, v1, v4, vcc
	v_sub_u32_e32 v4, v3, v2
	v_cndmask_b32_e32 v3, v3, v4, vcc
	v_add_u32_e32 v4, 1, v1
	v_cmp_ge_u32_e32 vcc, v3, v2
	v_add_u32_e32 v3, 1, v5
	s_nop 0
	v_cndmask_b32_e32 v1, v1, v4, vcc
	v_mul_lo_u32 v4, v2, v1
	v_add_u32_e32 v2, v4, v2
	v_cmp_ne_u32_e32 vcc, v3, v2
	s_and_saveexec_b64 s[2:3], vcc
	s_xor_b64 s[8:9], exec, s[2:3]
	s_cbranch_execz .LBB0_1094
	s_waitcnt lgkmcnt(0)
	v_mov_b32_e32 v0, 0x583100
	global_load_dword v0, v0, s[72:73] offset:1024 sc1
	s_add_u32 s14, s72, 0x583500
	s_addc_u32 s15, s73, 0
	s_waitcnt vmcnt(0)
	v_cmp_eq_u32_e32 vcc, v0, v1
	s_and_saveexec_b64 s[10:11], vcc
	s_cbranch_execz .LBB0_1093
	s_add_u32 s12, s72, 0x580200
	s_addc_u32 s13, s73, 0
	s_mov_b32 s2, 1
	s_mov_b64 s[16:17], 0
	v_mov_b32_e32 v0, 0
	s_branch .LBB0_1084

; __device__ __forceinline__ unsigned xb_ld(unsigned* p)              { return __hip_atomic_load(p, __ATOMIC_RELAXED, __HIP_MEMORY_SCOPE_AGENT); }
; __device__ __forceinline__ unsigned xb_add(unsigned* p, unsigned v) { return __hip_atomic_fetch_add(p, v, __ATOMIC_RELAXED, __HIP_MEMORY_SCOPE_AGENT); }
; #define XB_SPIN(cond, bar) do { unsigned _sp = 0; while (cond) { __builtin_amdgcn_s_sleep(1); \
;     if ((++_sp & 255u) == 0u) { if (xb_ld(&(bar)[XB_TMO])) break; if (_sp > XB_SPIN_CAP) { atomicAdd(&(bar)[XB_TMO], 1u); break; } } } } while (0)
; __device__ __forceinline__ void xcd_barrier(const XcdBarrier& b) {
;     ...
;         const unsigned old = xb_add(&bar[XB_XSUB(b.x)], 1u);
;         const unsigned gen = old / nloc;
;         if (old + 1u == (gen + 1u) * nloc) {
;             __builtin_amdgcn_fence(__ATOMIC_RELEASE, "agent");
;             asm volatile("s_waitcnt vmcnt(0)" ::: "memory");
;             const unsigned og = xb_add(&bar[XB_TOP], 1u);
;             const unsigned tg = og / nx;
;             if (og + 1u == (tg + 1u) * nx) xb_add(&bar[XB_TOPGEN], 1u);
;             else XB_SPIN(xb_ld(&bar[XB_TOPGEN]) == tg, bar);
;             __builtin_amdgcn_fence(__ATOMIC_ACQUIRE, "agent");
;             xb_add(&bar[XB_XGEN(b.x)], 1u);
;             asm volatile("s_waitcnt vmcnt(0)" ::: "memory");
;         } else {
;             XB_SPIN(xb_ld(&bar[XB_XGEN(b.x)]) == gen, bar);
;             __builtin_amdgcn_fence(__ATOMIC_ACQUIRE, "agent");
;             asm volatile("s_waitcnt vmcnt(0)" ::: "memory");
;         }
.LBB0_1271:
	s_or_b64 exec, exec, s[8:9]
	v_cvt_f32_u32_e32 v4, v2
	s_waitcnt vmcnt(0)
	v_readfirstlane_b32 s2, v3
	v_sub_u32_e32 v3, 0, v2
	v_rcp_iflag_f32_e32 v4, v4
	v_add_u32_e32 v5, s2, v1
	v_mul_f32_e32 v4, 0x4f7ffffe, v4
	v_cvt_u32_f32_e32 v4, v4
	v_mul_lo_u32 v1, v3, v4
	v_mul_hi_u32 v1, v4, v1
	v_add_u32_e32 v1, v4, v1
	v_mul_hi_u32 v1, v5, v1
	v_mul_lo_u32 v3, v1, v2
	v_sub_u32_e32 v3, v5, v3
	v_add_u32_e32 v4, 1, v1
	v_cmp_ge_u32_e32 vcc, v3, v2
	s_nop 1
	v_cndmask_b32_e32 v1, v1, v4, vcc
	v_sub_u32_e32 v4, v3, v2
	v_cndmask_b32_e32 v3, v3, v4, vcc
	v_add_u32_e32 v4, 1, v1
	v_cmp_ge_u32_e32 vcc, v3, v2
	v_add_u32_e32 v3, 1, v5
	s_nop 0
	v_cndmask_b32_e32 v1, v1, v4, vcc
	v_mul_lo_u32 v4, v2, v1
	v_add_u32_e32 v2, v4, v2
	v_cmp_ne_u32_e32 vcc, v3, v2
	s_and_saveexec_b64 s[2:3], vcc
	s_xor_b64 s[6:7], exec, s[2:3]
	s_cbranch_execz .LBB0_1285
	s_waitcnt lgkmcnt(0)
	v_mov_b32_e32 v0, 0x583100
	global_load_dword v0, v0, s[72:73] offset:1024 sc1
	s_add_u32 s14, s72, 0x583500
	s_addc_u32 s15, s73, 0
	s_waitcnt vmcnt(0)
	v_cmp_eq_u32_e32 vcc, v0, v1
	s_and_saveexec_b64 s[8:9], vcc
	s_cbranch_execz .LBB0_1284
	s_add_u32 s10, s72, 0x580200
	s_addc_u32 s11, s73, 0
	s_mov_b32 s2, 1
	s_mov_b64 s[16:17], 0
	v_mov_b32_e32 v0, 0
	s_branch .LBB0_1275
